# thin GEMM loads de-serialised + kv_prompt_out hand-written fast path (all chunks of a thread loaded together, shift arithmetic)
# baseline (speedup 1.0000x reference)
; __device__ __forceinline__ void unpack8(const v4u w, float (&f)[8]) { f[0] = bf_lo(w.x); f[1] = bf_hi(w.x); f[2] = bf_lo(w.y); f[3] = bf_hi(w.y); f[4] = bf_lo(w.z); f[5] = bf_hi(w.z); f[6] = bf_lo(w.w); f[7] = bf_hi(w.w); }
; __device__ __forceinline__ void kv_prompt_out(const Frame& F, CArgs* A, int j, const bf16* QKV) {
; #pragma unroll 4
;     for (int idx = F.gt; idx < 5376 * 256; idx += F.ngt) {
;         const int c = (idx & 127) * 8, kv = (idx >> 7) & 1; int rr = idx >> 8; int g, keep; size_t obase;
;         if (rr < 256) { g = 0; keep = 128; obase = O_KVP0; } else if (rr < 1280) { g = 1; keep = 512; rr -= 256; obase = O_KVP1; } else { g = 2; keep = 2048; rr -= 1280; obase = O_KVP2; }
;         const int b = rr / keep, r = rr - b * keep;
;         const int t = TSEQ - keep + r, dsh = 2 * g, pos = ((t & ((1 << dsh) - 1)) << (12 - dsh)) + (t >> dsh);
;         float x[8]; unpack8(*(const v4u*)(QKV + ((size_t)((g * 3 + 1 + kv) * 8 + (c >> 7)) * 2 + b) * (4096 * 128) + (size_t)pos * 128 + (c & 127)), x);
;         store8f(A->out + obase + (((size_t)(j * 2 + b) * keep + r) * 2 + kv) * 1024 + c, x);
;     }
.LBB0_1185:
	s_cmp_lg_u32 s59, 0x100
	s_cbranch_scc1 .Lkvo_orig
	v_readlane_b32 s0, v255, 33
	s_lshl_b32 s0, s0, 6
	s_lshl_b32 s1, s60, 9
	s_add_i32 s1, s1, s0
	v_readlane_b32 s12, v255, 34
	v_readlane_b32 s13, v255, 35
	s_waitcnt vmcnt(2)
	v_add_u32_e32 v20, s1, v138
	s_mov_b64 s[10:11], exec
	s_lshl_b32 s16, s67, 7
	s_lshl_b32 s20, s67, 9
	s_lshl_b32 s24, s67, 11
	s_load_dwordx2 s[12:13], s[12:13], 0xe0
	v_and_b32_e32 v21, 0x7f, v20
	v_bfe_u32 v22, v20, 7, 1
	v_lshrrev_b32_e32 v23, 8, v20
	v_lshrrev_b32_e32 v24, 4, v21
	v_lshl_add_u32 v25, v22, 3, v24
	v_and_b32_e32 v26, 15, v21
	v_lshlrev_b32_e32 v26, 4, v26
	v_lshl_or_b32 v27, v25, 21, v26
	v_add_u32_e32 v28, 0x1000000, v27
	v_add_u32_e32 v29, 0x4000000, v27
	v_add_u32_e32 v30, 0x7000000, v27
	v_lshlrev_b32_e32 v31, 5, v21
	v_lshl_or_b32 v31, v22, 12, v31
	v_add_u32_e32 v32, 0x4040000, v31
	v_add_u32_e32 v33, 0x4440000, v31
	v_add_u32_e32 v34, 0x5440000, v31
	s_cmp_lt_u32 s60, 0x80
	s_cbranch_scc0 .Lkvo_b
	v_add_u32_e32 v35, 0x0, v23
	v_lshrrev_b32_e32 v36, 7, v35
	v_and_b32_e32 v37, 0x7f, v35
	v_or_b32_e32 v37, 0xf80, v37
	v_lshl_add_u32 v39, v36, 20, v28
	v_lshl_add_u32 v39, v37, 8, v39
	global_load_dwordx4 v[84:87], v39, s[2:3]
	v_add_u32_e32 v35, s16, v35
	v_lshl_add_u32 v140, v35, 13, v32
	v_add_u32_e32 v35, 0x100, v23
	v_lshrrev_b32_e32 v36, 9, v35
	v_and_b32_e32 v37, 0x1ff, v35
	v_or_b32_e32 v37, 0xe00, v37
	v_and_b32_e32 v38, 3, v37
	v_lshrrev_b32_e32 v37, 2, v37
	v_lshl_or_b32 v38, v38, 10, v37
	v_lshl_add_u32 v39, v36, 20, v29
	v_lshl_add_u32 v39, v38, 8, v39
	global_load_dwordx4 v[88:91], v39, s[2:3]
	v_add_u32_e32 v35, s20, v35
	v_lshl_add_u32 v141, v35, 13, v33
	v_add_u32_e32 v35, 0x300, v23
	v_lshrrev_b32_e32 v36, 9, v35
	v_and_b32_e32 v37, 0x1ff, v35
	v_or_b32_e32 v37, 0xe00, v37
	v_and_b32_e32 v38, 3, v37
	v_lshrrev_b32_e32 v37, 2, v37
	v_lshl_or_b32 v38, v38, 10, v37
	v_lshl_add_u32 v39, v36, 20, v29
	v_lshl_add_u32 v39, v38, 8, v39
	global_load_dwordx4 v[92:95], v39, s[2:3]
	v_add_u32_e32 v35, s20, v35
	v_lshl_add_u32 v142, v35, 13, v33
	v_add_u32_e32 v35, 0x100, v23
	v_lshrrev_b32_e32 v36, 11, v35
	v_and_b32_e32 v37, 0x7ff, v35
	v_or_b32_e32 v37, 0x800, v37
	v_and_b32_e32 v38, 15, v37
	v_lshrrev_b32_e32 v37, 4, v37
	v_lshl_or_b32 v38, v38, 8, v37
	v_lshl_add_u32 v39, v36, 20, v30
	v_lshl_add_u32 v39, v38, 8, v39
	global_load_dwordx4 v[96:99], v39, s[2:3]
	v_add_u32_e32 v35, s24, v35
	v_lshl_add_u32 v143, v35, 13, v34
	v_add_u32_e32 v35, 0x300, v23
	v_lshrrev_b32_e32 v36, 11, v35
	v_and_b32_e32 v37, 0x7ff, v35
	v_or_b32_e32 v37, 0x800, v37
	v_and_b32_e32 v38, 15, v37
	v_lshrrev_b32_e32 v37, 4, v37
	v_lshl_or_b32 v38, v38, 8, v37
	v_lshl_add_u32 v39, v36, 20, v30
	v_lshl_add_u32 v39, v38, 8, v39
	global_load_dwordx4 v[100:103], v39, s[2:3]
	v_add_u32_e32 v35, s24, v35
	v_lshl_add_u32 v144, v35, 13, v34
	v_add_u32_e32 v35, 0x500, v23
	v_lshrrev_b32_e32 v36, 11, v35
	v_and_b32_e32 v37, 0x7ff, v35
	v_or_b32_e32 v37, 0x800, v37
	v_and_b32_e32 v38, 15, v37
	v_lshrrev_b32_e32 v37, 4, v37
	v_lshl_or_b32 v38, v38, 8, v37
	v_lshl_add_u32 v39, v36, 20, v30
	v_lshl_add_u32 v39, v38, 8, v39
	global_load_dwordx4 v[104:107], v39, s[2:3]
	v_add_u32_e32 v35, s24, v35
	v_lshl_add_u32 v145, v35, 13, v34
	v_add_u32_e32 v35, 0x700, v23
	v_lshrrev_b32_e32 v36, 11, v35
	v_and_b32_e32 v37, 0x7ff, v35
	v_or_b32_e32 v37, 0x800, v37
	v_and_b32_e32 v38, 15, v37
	v_lshrrev_b32_e32 v37, 4, v37
	v_lshl_or_b32 v38, v38, 8, v37
	v_lshl_add_u32 v39, v36, 20, v30
	v_lshl_add_u32 v39, v38, 8, v39
	global_load_dwordx4 v[108:111], v39, s[2:3]
	v_add_u32_e32 v35, s24, v35
	v_lshl_add_u32 v146, v35, 13, v34
	v_add_u32_e32 v35, 0x900, v23
	v_lshrrev_b32_e32 v36, 11, v35
	v_and_b32_e32 v37, 0x7ff, v35
	v_or_b32_e32 v37, 0x800, v37
	v_and_b32_e32 v38, 15, v37
	v_lshrrev_b32_e32 v37, 4, v37
	v_lshl_or_b32 v38, v38, 8, v37
	v_lshl_add_u32 v39, v36, 20, v30
	v_lshl_add_u32 v39, v38, 8, v39
	global_load_dwordx4 v[112:115], v39, s[2:3]
	v_add_u32_e32 v35, s24, v35
	v_lshl_add_u32 v147, v35, 13, v34
	v_add_u32_e32 v35, 0xb00, v23
	v_lshrrev_b32_e32 v36, 11, v35
	v_and_b32_e32 v37, 0x7ff, v35
	v_or_b32_e32 v37, 0x800, v37
	v_and_b32_e32 v38, 15, v37
	v_lshrrev_b32_e32 v37, 4, v37
	v_lshl_or_b32 v38, v38, 8, v37
	v_lshl_add_u32 v39, v36, 20, v30
	v_lshl_add_u32 v39, v38, 8, v39
	global_load_dwordx4 v[116:119], v39, s[2:3]
	v_add_u32_e32 v35, s24, v35
	v_lshl_add_u32 v148, v35, 13, v34
	v_add_u32_e32 v35, 0xd00, v23
	v_lshrrev_b32_e32 v36, 11, v35
	v_and_b32_e32 v37, 0x7ff, v35
	v_or_b32_e32 v37, 0x800, v37
	v_and_b32_e32 v38, 15, v37
	v_lshrrev_b32_e32 v37, 4, v37
	v_lshl_or_b32 v38, v38, 8, v37
	v_lshl_add_u32 v39, v36, 20, v30
	v_lshl_add_u32 v39, v38, 8, v39
	global_load_dwordx4 v[120:123], v39, s[2:3]
	v_add_u32_e32 v35, s24, v35
	v_lshl_add_u32 v149, v35, 13, v34
	v_add_u32_e32 v35, 0xf00, v23
	v_lshrrev_b32_e32 v36, 11, v35
	v_and_b32_e32 v37, 0x7ff, v35
	v_or_b32_e32 v37, 0x800, v37
	v_and_b32_e32 v38, 15, v37
	v_lshrrev_b32_e32 v37, 4, v37
	v_lshl_or_b32 v38, v38, 8, v37
	v_lshl_add_u32 v39, v36, 20, v30
	v_lshl_add_u32 v39, v38, 8, v39
	global_load_dwordx4 v[124:127], v39, s[2:3]
	v_add_u32_e32 v35, s24, v35
	v_lshl_add_u32 v150, v35, 13, v34
	s_waitcnt lgkmcnt(0)
	s_waitcnt vmcnt(10)
	v_lshlrev_b32_e32 v40, 16, v84
	v_and_b32_e32 v41, 0xffff0000, v84
	v_lshlrev_b32_e32 v42, 16, v85
	v_and_b32_e32 v43, 0xffff0000, v85
	v_lshlrev_b32_e32 v44, 16, v86
	v_and_b32_e32 v45, 0xffff0000, v86
	v_lshlrev_b32_e32 v46, 16, v87
	v_and_b32_e32 v47, 0xffff0000, v87
	global_store_dwordx4 v140, v[40:43], s[12:13]
	global_store_dwordx4 v140, v[44:47], s[12:13] offset:16
	s_waitcnt vmcnt(11)
; __device__ __forceinline__ void unpack8(const v4u w, float (&f)[8]) { f[0] = bf_lo(w.x); f[1] = bf_hi(w.x); f[2] = bf_lo(w.y); f[3] = bf_hi(w.y); f[4] = bf_lo(w.z); f[5] = bf_hi(w.z); f[6] = bf_lo(w.w); f[7] = bf_hi(w.w); }
; __device__ __forceinline__ void kv_prompt_out(const Frame& F, CArgs* A, int j, const bf16* QKV) {
;     ...
;     for (int idx = F.gt; idx < 5376 * 256; idx += F.ngt) {
;         const int c = (idx & 127) * 8, kv = (idx >> 7) & 1; int rr = idx >> 8; int g, keep; size_t obase;
;         if (rr < 256) { g = 0; keep = 128; obase = O_KVP0; } else if (rr < 1280) { g = 1; keep = 512; rr -= 256; obase = O_KVP1; } else { g = 2; keep = 2048; rr -= 1280; obase = O_KVP2; }
;         const int b = rr / keep, r = rr - b * keep;
;         const int t = TSEQ - keep + r, dsh = 2 * g, pos = ((t & ((1 << dsh) - 1)) << (12 - dsh)) + (t >> dsh);
;         float x[8]; unpack8(*(const v4u*)(QKV + ((size_t)((g * 3 + 1 + kv) * 8 + (c >> 7)) * 2 + b) * (4096 * 128) + (size_t)pos * 128 + (c & 127)), x);
;         store8f(A->out + obase + (((size_t)(j * 2 + b) * keep + r) * 2 + kv) * 1024 + c, x);
;     }
	v_lshlrev_b32_e32 v48, 16, v88
	v_and_b32_e32 v49, 0xffff0000, v88
	v_lshlrev_b32_e32 v50, 16, v89
	v_and_b32_e32 v51, 0xffff0000, v89
	v_lshlrev_b32_e32 v52, 16, v90
	v_and_b32_e32 v53, 0xffff0000, v90
	v_lshlrev_b32_e32 v54, 16, v91
	v_and_b32_e32 v55, 0xffff0000, v91
	global_store_dwordx4 v141, v[48:51], s[12:13]
	global_store_dwordx4 v141, v[52:55], s[12:13] offset:16
	s_waitcnt vmcnt(12)
	v_lshlrev_b32_e32 v56, 16, v92
	v_and_b32_e32 v57, 0xffff0000, v92
	v_lshlrev_b32_e32 v58, 16, v93
	v_and_b32_e32 v59, 0xffff0000, v93
	v_lshlrev_b32_e32 v60, 16, v94
	v_and_b32_e32 v61, 0xffff0000, v94
	v_lshlrev_b32_e32 v62, 16, v95
	v_and_b32_e32 v63, 0xffff0000, v95
	global_store_dwordx4 v142, v[56:59], s[12:13]
	global_store_dwordx4 v142, v[60:63], s[12:13] offset:16
	s_waitcnt vmcnt(13)
	v_lshlrev_b32_e32 v40, 16, v96
	v_and_b32_e32 v41, 0xffff0000, v96
	v_lshlrev_b32_e32 v42, 16, v97
	v_and_b32_e32 v43, 0xffff0000, v97
	v_lshlrev_b32_e32 v44, 16, v98
	v_and_b32_e32 v45, 0xffff0000, v98
	v_lshlrev_b32_e32 v46, 16, v99
	v_and_b32_e32 v47, 0xffff0000, v99
	global_store_dwordx4 v143, v[40:43], s[12:13]
	global_store_dwordx4 v143, v[44:47], s[12:13] offset:16
	s_waitcnt vmcnt(14)
	v_lshlrev_b32_e32 v48, 16, v100
	v_and_b32_e32 v49, 0xffff0000, v100
	v_lshlrev_b32_e32 v50, 16, v101
	v_and_b32_e32 v51, 0xffff0000, v101
	v_lshlrev_b32_e32 v52, 16, v102
	v_and_b32_e32 v53, 0xffff0000, v102
	v_lshlrev_b32_e32 v54, 16, v103
	v_and_b32_e32 v55, 0xffff0000, v103
	global_store_dwordx4 v144, v[48:51], s[12:13]
	global_store_dwordx4 v144, v[52:55], s[12:13] offset:16
	s_waitcnt vmcnt(15)
	v_lshlrev_b32_e32 v56, 16, v104
	v_and_b32_e32 v57, 0xffff0000, v104
	v_lshlrev_b32_e32 v58, 16, v105
	v_and_b32_e32 v59, 0xffff0000, v105
	v_lshlrev_b32_e32 v60, 16, v106
	v_and_b32_e32 v61, 0xffff0000, v106
	v_lshlrev_b32_e32 v62, 16, v107
	v_and_b32_e32 v63, 0xffff0000, v107
	global_store_dwordx4 v145, v[56:59], s[12:13]
	global_store_dwordx4 v145, v[60:63], s[12:13] offset:16
	s_waitcnt vmcnt(16)
	v_lshlrev_b32_e32 v40, 16, v108
	v_and_b32_e32 v41, 0xffff0000, v108
	v_lshlrev_b32_e32 v42, 16, v109
	v_and_b32_e32 v43, 0xffff0000, v109
	v_lshlrev_b32_e32 v44, 16, v110
	v_and_b32_e32 v45, 0xffff0000, v110
	v_lshlrev_b32_e32 v46, 16, v111
	v_and_b32_e32 v47, 0xffff0000, v111
	global_store_dwordx4 v146, v[40:43], s[12:13]
	global_store_dwordx4 v146, v[44:47], s[12:13] offset:16
	s_waitcnt vmcnt(17)
	v_lshlrev_b32_e32 v48, 16, v112
	v_and_b32_e32 v49, 0xffff0000, v112
	v_lshlrev_b32_e32 v50, 16, v113
	v_and_b32_e32 v51, 0xffff0000, v113
	v_lshlrev_b32_e32 v52, 16, v114
	v_and_b32_e32 v53, 0xffff0000, v114
	v_lshlrev_b32_e32 v54, 16, v115
	v_and_b32_e32 v55, 0xffff0000, v115
	global_store_dwordx4 v147, v[48:51], s[12:13]
	global_store_dwordx4 v147, v[52:55], s[12:13] offset:16
	s_waitcnt vmcnt(18)
	v_lshlrev_b32_e32 v56, 16, v116
	v_and_b32_e32 v57, 0xffff0000, v116
	v_lshlrev_b32_e32 v58, 16, v117
	v_and_b32_e32 v59, 0xffff0000, v117
	v_lshlrev_b32_e32 v60, 16, v118
	v_and_b32_e32 v61, 0xffff0000, v118
	v_lshlrev_b32_e32 v62, 16, v119
	v_and_b32_e32 v63, 0xffff0000, v119
	global_store_dwordx4 v148, v[56:59], s[12:13]
	global_store_dwordx4 v148, v[60:63], s[12:13] offset:16
	s_waitcnt vmcnt(19)
	v_lshlrev_b32_e32 v40, 16, v120
	v_and_b32_e32 v41, 0xffff0000, v120
	v_lshlrev_b32_e32 v42, 16, v121
	v_and_b32_e32 v43, 0xffff0000, v121
	v_lshlrev_b32_e32 v44, 16, v122
	v_and_b32_e32 v45, 0xffff0000, v122
	v_lshlrev_b32_e32 v46, 16, v123
	v_and_b32_e32 v47, 0xffff0000, v123
	global_store_dwordx4 v149, v[40:43], s[12:13]
	global_store_dwordx4 v149, v[44:47], s[12:13] offset:16
	s_waitcnt vmcnt(20)
	v_lshlrev_b32_e32 v48, 16, v124
	v_and_b32_e32 v49, 0xffff0000, v124
	v_lshlrev_b32_e32 v50, 16, v125
	v_and_b32_e32 v51, 0xffff0000, v125
	v_lshlrev_b32_e32 v52, 16, v126
	v_and_b32_e32 v53, 0xffff0000, v126
	v_lshlrev_b32_e32 v54, 16, v127
	v_and_b32_e32 v55, 0xffff0000, v127
	global_store_dwordx4 v150, v[48:51], s[12:13]
	global_store_dwordx4 v150, v[52:55], s[12:13] offset:16
	s_branch .LBB0_1223
.Lkvo_b:
	v_subrev_u32_e32 v35, 0x100, v23
	v_lshrrev_b32_e32 v36, 9, v35
	v_and_b32_e32 v37, 0x1ff, v35
	v_or_b32_e32 v37, 0xe00, v37
	v_and_b32_e32 v38, 3, v37
	v_lshrrev_b32_e32 v37, 2, v37
	v_lshl_or_b32 v38, v38, 10, v37
	v_lshl_add_u32 v39, v36, 20, v29
	v_lshl_add_u32 v39, v38, 8, v39
	global_load_dwordx4 v[84:87], v39, s[2:3]
	v_add_u32_e32 v35, s20, v35
	v_lshl_add_u32 v140, v35, 13, v33
	v_add_u32_e32 v35, 0x100, v23
	v_lshrrev_b32_e32 v36, 9, v35
	v_and_b32_e32 v37, 0x1ff, v35
	v_or_b32_e32 v37, 0xe00, v37
	v_and_b32_e32 v38, 3, v37
	v_lshrrev_b32_e32 v37, 2, v37
	v_lshl_or_b32 v38, v38, 10, v37
	v_lshl_add_u32 v39, v36, 20, v29
	v_lshl_add_u32 v39, v38, 8, v39
	global_load_dwordx4 v[88:91], v39, s[2:3]
	v_add_u32_e32 v35, s20, v35
	v_lshl_add_u32 v141, v35, 13, v33
	v_subrev_u32_e32 v35, 0x100, v23
	v_lshrrev_b32_e32 v36, 11, v35
	v_and_b32_e32 v37, 0x7ff, v35
	v_or_b32_e32 v37, 0x800, v37
	v_and_b32_e32 v38, 15, v37
	v_lshrrev_b32_e32 v37, 4, v37
	v_lshl_or_b32 v38, v38, 8, v37
	v_lshl_add_u32 v39, v36, 20, v30
	v_lshl_add_u32 v39, v38, 8, v39
	global_load_dwordx4 v[92:95], v39, s[2:3]
	v_add_u32_e32 v35, s24, v35
	v_lshl_add_u32 v142, v35, 13, v34
	v_add_u32_e32 v35, 0x100, v23
	v_lshrrev_b32_e32 v36, 11, v35
	v_and_b32_e32 v37, 0x7ff, v35
	v_or_b32_e32 v37, 0x800, v37
	v_and_b32_e32 v38, 15, v37
	v_lshrrev_b32_e32 v37, 4, v37
	v_lshl_or_b32 v38, v38, 8, v37
	v_lshl_add_u32 v39, v36, 20, v30
	v_lshl_add_u32 v39, v38, 8, v39
	global_load_dwordx4 v[96:99], v39, s[2:3]
	v_add_u32_e32 v35, s24, v35
	v_lshl_add_u32 v143, v35, 13, v34
	v_add_u32_e32 v35, 0x300, v23
; __device__ __forceinline__ void unpack8(const v4u w, float (&f)[8]) { f[0] = bf_lo(w.x); f[1] = bf_hi(w.x); f[2] = bf_lo(w.y); f[3] = bf_hi(w.y); f[4] = bf_lo(w.z); f[5] = bf_hi(w.z); f[6] = bf_lo(w.w); f[7] = bf_hi(w.w); }
; __device__ __forceinline__ void kv_prompt_out(const Frame& F, CArgs* A, int j, const bf16* QKV) {
;     ...
;     for (int idx = F.gt; idx < 5376 * 256; idx += F.ngt) {
;         const int c = (idx & 127) * 8, kv = (idx >> 7) & 1; int rr = idx >> 8; int g, keep; size_t obase;
;         if (rr < 256) { g = 0; keep = 128; obase = O_KVP0; } else if (rr < 1280) { g = 1; keep = 512; rr -= 256; obase = O_KVP1; } else { g = 2; keep = 2048; rr -= 1280; obase = O_KVP2; }
;         const int b = rr / keep, r = rr - b * keep;
;         const int t = TSEQ - keep + r, dsh = 2 * g, pos = ((t & ((1 << dsh) - 1)) << (12 - dsh)) + (t >> dsh);
;         float x[8]; unpack8(*(const v4u*)(QKV + ((size_t)((g * 3 + 1 + kv) * 8 + (c >> 7)) * 2 + b) * (4096 * 128) + (size_t)pos * 128 + (c & 127)), x);
;         store8f(A->out + obase + (((size_t)(j * 2 + b) * keep + r) * 2 + kv) * 1024 + c, x);
;     }
	v_lshrrev_b32_e32 v36, 11, v35
	v_and_b32_e32 v37, 0x7ff, v35
	v_or_b32_e32 v37, 0x800, v37
	v_and_b32_e32 v38, 15, v37
	v_lshrrev_b32_e32 v37, 4, v37
	v_lshl_or_b32 v38, v38, 8, v37
	v_lshl_add_u32 v39, v36, 20, v30
	v_lshl_add_u32 v39, v38, 8, v39
	global_load_dwordx4 v[100:103], v39, s[2:3]
	v_add_u32_e32 v35, s24, v35
	v_lshl_add_u32 v144, v35, 13, v34
	v_add_u32_e32 v35, 0x500, v23
	v_lshrrev_b32_e32 v36, 11, v35
	v_and_b32_e32 v37, 0x7ff, v35
	v_or_b32_e32 v37, 0x800, v37
	v_and_b32_e32 v38, 15, v37
	v_lshrrev_b32_e32 v37, 4, v37
	v_lshl_or_b32 v38, v38, 8, v37
	v_lshl_add_u32 v39, v36, 20, v30
	v_lshl_add_u32 v39, v38, 8, v39
	global_load_dwordx4 v[104:107], v39, s[2:3]
	v_add_u32_e32 v35, s24, v35
	v_lshl_add_u32 v145, v35, 13, v34
	v_add_u32_e32 v35, 0x700, v23
	v_lshrrev_b32_e32 v36, 11, v35
	v_and_b32_e32 v37, 0x7ff, v35
	v_or_b32_e32 v37, 0x800, v37
	v_and_b32_e32 v38, 15, v37
	v_lshrrev_b32_e32 v37, 4, v37
	v_lshl_or_b32 v38, v38, 8, v37
	v_lshl_add_u32 v39, v36, 20, v30
	v_lshl_add_u32 v39, v38, 8, v39
	global_load_dwordx4 v[108:111], v39, s[2:3]
	v_add_u32_e32 v35, s24, v35
	v_lshl_add_u32 v146, v35, 13, v34
	v_add_u32_e32 v35, 0x900, v23
	v_lshrrev_b32_e32 v36, 11, v35
	v_and_b32_e32 v37, 0x7ff, v35
	v_or_b32_e32 v37, 0x800, v37
	v_and_b32_e32 v38, 15, v37
	v_lshrrev_b32_e32 v37, 4, v37
	v_lshl_or_b32 v38, v38, 8, v37
	v_lshl_add_u32 v39, v36, 20, v30
	v_lshl_add_u32 v39, v38, 8, v39
	global_load_dwordx4 v[112:115], v39, s[2:3]
	v_add_u32_e32 v35, s24, v35
	v_lshl_add_u32 v147, v35, 13, v34
	v_add_u32_e32 v35, 0xb00, v23
	v_lshrrev_b32_e32 v36, 11, v35
	v_and_b32_e32 v37, 0x7ff, v35
	v_or_b32_e32 v37, 0x800, v37
	v_and_b32_e32 v38, 15, v37
	v_lshrrev_b32_e32 v37, 4, v37
	v_lshl_or_b32 v38, v38, 8, v37
	v_lshl_add_u32 v39, v36, 20, v30
	v_lshl_add_u32 v39, v38, 8, v39
	global_load_dwordx4 v[116:119], v39, s[2:3]
	v_add_u32_e32 v35, s24, v35
	v_lshl_add_u32 v148, v35, 13, v34
	v_add_u32_e32 v35, 0xd00, v23
	v_lshrrev_b32_e32 v36, 11, v35
	v_and_b32_e32 v37, 0x7ff, v35
	v_or_b32_e32 v37, 0x800, v37
	v_and_b32_e32 v38, 15, v37
	v_lshrrev_b32_e32 v37, 4, v37
	v_lshl_or_b32 v38, v38, 8, v37
	v_lshl_add_u32 v39, v36, 20, v30
	v_lshl_add_u32 v39, v38, 8, v39
	global_load_dwordx4 v[120:123], v39, s[2:3]
	v_add_u32_e32 v35, s24, v35
	v_lshl_add_u32 v149, v35, 13, v34
	s_waitcnt lgkmcnt(0)
	s_waitcnt vmcnt(9)
	v_lshlrev_b32_e32 v40, 16, v84
	v_and_b32_e32 v41, 0xffff0000, v84
	v_lshlrev_b32_e32 v42, 16, v85
	v_and_b32_e32 v43, 0xffff0000, v85
	v_lshlrev_b32_e32 v44, 16, v86
	v_and_b32_e32 v45, 0xffff0000, v86
	v_lshlrev_b32_e32 v46, 16, v87
	v_and_b32_e32 v47, 0xffff0000, v87
	global_store_dwordx4 v140, v[40:43], s[12:13]
	global_store_dwordx4 v140, v[44:47], s[12:13] offset:16
	s_waitcnt vmcnt(10)
	v_lshlrev_b32_e32 v48, 16, v88
	v_and_b32_e32 v49, 0xffff0000, v88
	v_lshlrev_b32_e32 v50, 16, v89
	v_and_b32_e32 v51, 0xffff0000, v89
	v_lshlrev_b32_e32 v52, 16, v90
	v_and_b32_e32 v53, 0xffff0000, v90
	v_lshlrev_b32_e32 v54, 16, v91
	v_and_b32_e32 v55, 0xffff0000, v91
	global_store_dwordx4 v141, v[48:51], s[12:13]
	global_store_dwordx4 v141, v[52:55], s[12:13] offset:16
	s_waitcnt vmcnt(11)
	v_lshlrev_b32_e32 v56, 16, v92
	v_and_b32_e32 v57, 0xffff0000, v92
	v_lshlrev_b32_e32 v58, 16, v93
	v_and_b32_e32 v59, 0xffff0000, v93
	v_lshlrev_b32_e32 v60, 16, v94
	v_and_b32_e32 v61, 0xffff0000, v94
	v_lshlrev_b32_e32 v62, 16, v95
	v_and_b32_e32 v63, 0xffff0000, v95
	global_store_dwordx4 v142, v[56:59], s[12:13]
	global_store_dwordx4 v142, v[60:63], s[12:13] offset:16
	s_waitcnt vmcnt(12)
	v_lshlrev_b32_e32 v40, 16, v96
	v_and_b32_e32 v41, 0xffff0000, v96
	v_lshlrev_b32_e32 v42, 16, v97
	v_and_b32_e32 v43, 0xffff0000, v97
	v_lshlrev_b32_e32 v44, 16, v98
	v_and_b32_e32 v45, 0xffff0000, v98
	v_lshlrev_b32_e32 v46, 16, v99
	v_and_b32_e32 v47, 0xffff0000, v99
	global_store_dwordx4 v143, v[40:43], s[12:13]
	global_store_dwordx4 v143, v[44:47], s[12:13] offset:16
	s_waitcnt vmcnt(13)
	v_lshlrev_b32_e32 v48, 16, v100
	v_and_b32_e32 v49, 0xffff0000, v100
	v_lshlrev_b32_e32 v50, 16, v101
	v_and_b32_e32 v51, 0xffff0000, v101
	v_lshlrev_b32_e32 v52, 16, v102
	v_and_b32_e32 v53, 0xffff0000, v102
	v_lshlrev_b32_e32 v54, 16, v103
	v_and_b32_e32 v55, 0xffff0000, v103
	global_store_dwordx4 v144, v[48:51], s[12:13]
	global_store_dwordx4 v144, v[52:55], s[12:13] offset:16
	s_waitcnt vmcnt(14)
	v_lshlrev_b32_e32 v56, 16, v104
	v_and_b32_e32 v57, 0xffff0000, v104
	v_lshlrev_b32_e32 v58, 16, v105
	v_and_b32_e32 v59, 0xffff0000, v105
	v_lshlrev_b32_e32 v60, 16, v106
	v_and_b32_e32 v61, 0xffff0000, v106
	v_lshlrev_b32_e32 v62, 16, v107
	v_and_b32_e32 v63, 0xffff0000, v107
	global_store_dwordx4 v145, v[56:59], s[12:13]
	global_store_dwordx4 v145, v[60:63], s[12:13] offset:16
	s_waitcnt vmcnt(15)
	v_lshlrev_b32_e32 v40, 16, v108
	v_and_b32_e32 v41, 0xffff0000, v108
	v_lshlrev_b32_e32 v42, 16, v109
	v_and_b32_e32 v43, 0xffff0000, v109
	v_lshlrev_b32_e32 v44, 16, v110
	v_and_b32_e32 v45, 0xffff0000, v110
	v_lshlrev_b32_e32 v46, 16, v111
	v_and_b32_e32 v47, 0xffff0000, v111
	global_store_dwordx4 v146, v[40:43], s[12:13]
	global_store_dwordx4 v146, v[44:47], s[12:13] offset:16
	s_waitcnt vmcnt(16)
	v_lshlrev_b32_e32 v48, 16, v112
	v_and_b32_e32 v49, 0xffff0000, v112
	v_lshlrev_b32_e32 v50, 16, v113
	v_and_b32_e32 v51, 0xffff0000, v113
	v_lshlrev_b32_e32 v52, 16, v114
	v_and_b32_e32 v53, 0xffff0000, v114
	v_lshlrev_b32_e32 v54, 16, v115
	v_and_b32_e32 v55, 0xffff0000, v115
	global_store_dwordx4 v147, v[48:51], s[12:13]
	global_store_dwordx4 v147, v[52:55], s[12:13] offset:16
	s_waitcnt vmcnt(17)
	v_lshlrev_b32_e32 v56, 16, v116
	v_and_b32_e32 v57, 0xffff0000, v116
	v_lshlrev_b32_e32 v58, 16, v117
	v_and_b32_e32 v59, 0xffff0000, v117
	v_lshlrev_b32_e32 v60, 16, v118
	v_and_b32_e32 v61, 0xffff0000, v118
	v_lshlrev_b32_e32 v62, 16, v119
	v_and_b32_e32 v63, 0xffff0000, v119
	global_store_dwordx4 v148, v[56:59], s[12:13]
	global_store_dwordx4 v148, v[60:63], s[12:13] offset:16
	s_waitcnt vmcnt(18)
	v_lshlrev_b32_e32 v40, 16, v120
	v_and_b32_e32 v41, 0xffff0000, v120
	v_lshlrev_b32_e32 v42, 16, v121
	v_and_b32_e32 v43, 0xffff0000, v121
	v_lshlrev_b32_e32 v44, 16, v122
	v_and_b32_e32 v45, 0xffff0000, v122
	v_lshlrev_b32_e32 v46, 16, v123
	v_and_b32_e32 v47, 0xffff0000, v123
	global_store_dwordx4 v149, v[40:43], s[12:13]
	global_store_dwordx4 v149, v[44:47], s[12:13] offset:16
	s_branch .LBB0_1223
